# GLA pair_tiles via v_permlane16_swap + 144 B dead padding so every later loop keeps v44's byte placement
# baseline (speedup 1.0000x reference)
; #define LAS __attribute__((address_space(3)))
; __device__ __forceinline__ unsigned pk2(float lo, float hi) { f32x2 v = {lo, hi}; bf16x2_t b = __builtin_convertvector(v, bf16x2_t); return __builtin_bit_cast(unsigned, b); }
; #define MFMA16(a, b, c) __builtin_amdgcn_mfma_f32_16x16x32_bf16((a), (b), (c), 0, 0, 0)
; #define LDS_BARRIER() asm volatile("s_waitcnt lgkmcnt(0)\n\ts_barrier" ::: "memory")
; __device__ __forceinline__ void gla_phase(LAS unsigned char* lds, const bf16_t* P, const float* hn, bf16_t* O, int G, int wg) {
;     ...
;             { const int st = wid & 3, tA = (wid >> 2) * 2;
;               bf16x8 kA[4], qA[2][4], qB[4], sB[4][4];
; #pragma unroll
;               for (int ks = 0; ks < 4; ++ks) { kA[ks] = FRAGK(KT, st, ks); qA[0][ks] = FRAGK(QT, tA, ks); qA[1][ks] = FRAGK(QT, tA + 1, ks); }
; #pragma unroll
;               for (int ks = 0; ks < 4; ++ks) qB[ks] = FRAGK(QT, tt, ks);
;               __builtin_amdgcn_sched_barrier(0);
;               f32x4 accA[2];
; #pragma unroll
;               for (int z = 0; z < 2; ++z) { accA[z] = (f32x4){0.f, 0.f, 0.f, 0.f};
;                 if (tA + z >= st) {
; #pragma unroll
;                     for (int ks = 0; ks < 4; ++ks) accA[z] = MFMA16(kA[ks], qA[z][ks], accA[z]);
;                 } }
;               __builtin_amdgcn_sched_barrier(0);
; #pragma unroll
;               for (int i = 0; i < 4; ++i)
; #pragma unroll
;                 for (int ks = 0; ks < 4; ++ks) sB[i][ks] = FRAGK(ST, eh * 4 + i, ks);
;               __builtin_amdgcn_sched_barrier(0);
; #pragma unroll
;               for (int z = 0; z < 2; ++z) { const int t = (tA + z) * 16 + fr, s0_ = st * 16 + fq * 4;
;                 u32x2 w; w.x = pk2(t >= s0_ ? accA[z][0] : 0.f, t >= s0_ + 1 ? accA[z][1] : 0.f); w.y = pk2(t >= s0_ + 2 ? accA[z][2] : 0.f, t >= s0_ + 3 ? accA[z][3] : 0.f);
;                 *(LAS u32x2*)(lds + AM + t * 128 + ((((st * 2 + (fq >> 1))) ^ ((fr >> 1) & 7)) << 4) + (fq & 1) * 8) = w; }
; #pragma unroll
;               for (int i = 0; i < 4; ++i) { oacc[i] = (f32x4){0.f, 0.f, 0.f, 0.f};
; #pragma unroll
;                 for (int ks = 0; ks < 4; ++ks) oacc[i] = MFMA16(sB[i][ks], qB[ks], oacc[i]); }
;             }
;             LDS_BARRIER();
.LBB0_1412:
	s_or_b64 exec, exec, vcc
	s_waitcnt lgkmcnt(11)
	v_add_u32_e32 v60, v152, v144
	s_waitcnt lgkmcnt(5)
	v_add_u32_e32 v68, v152, v157
	v_add_u32_e32 v76, v152, v158
	v_add_u32_e32 v95, v152, v159
	ds_read_b128 v[20:23], v60 offset:32768
	ds_read_b128 v[28:31], v60 offset:36864
	ds_read_b128 v[32:35], v68 offset:32768
	ds_read_b128 v[36:39], v68 offset:36864
	ds_read_b128 v[40:43], v76 offset:32768
	ds_read_b128 v[44:47], v76 offset:36864
	ds_read_b128 v[48:51], v95 offset:32768
	s_waitcnt lgkmcnt(11)
	ds_read_b128 v[52:55], v95 offset:36864
	ds_read_b128 v[56:59], v60 offset:40960
	ds_read_b128 v[60:63], v60 offset:45056
	ds_read_b128 v[64:67], v68 offset:40960
	ds_read_b128 v[68:71], v68 offset:45056
	ds_read_b128 v[72:75], v76 offset:40960
	ds_read_b128 v[76:79], v76 offset:45056
	ds_read_b128 v[218:221], v95 offset:40960
	ds_read_b128 v[222:225], v95 offset:45056
	v_cndmask_b32_e64 v16, v16, 0, s[72:73]
	v_cndmask_b32_e64 v17, 0, v17, s[74:75]
	v_cvt_pk_bf16_f32 v16, v16, v17
	v_cndmask_b32_e64 v17, v18, 0, s[76:77]
	v_cndmask_b32_e64 v18, v19, 0, s[78:79]
	v_cvt_pk_bf16_f32 v17, v17, v18
	ds_write_b64 v181, v[16:17]
	s_waitcnt lgkmcnt(14)
	v_mfma_f32_16x16x32_bf16 v[16:19], v[20:23], v[0:3], 0
	v_cndmask_b32_e64 v24, v24, 0, s[64:65]
	v_cndmask_b32_e64 v25, 0, v25, s[66:67]
	v_cvt_pk_bf16_f32 v24, v24, v25
	v_mfma_f32_16x16x32_bf16 v[20:23], v[28:31], v[0:3], 0
	v_cndmask_b32_e64 v25, v26, 0, s[68:69]
	v_cndmask_b32_e64 v26, v27, 0, s[70:71]
	v_cvt_pk_bf16_f32 v25, v25, v26
	ds_write_b64 v180, v[24:25]
	v_mfma_f32_16x16x32_bf16 v[16:19], v[32:35], v[4:7], v[16:19]
	s_waitcnt lgkmcnt(0)
	s_barrier
; #define LAS __attribute__((address_space(3)))
; #define MFMA16(a, b, c) __builtin_amdgcn_mfma_f32_16x16x32_bf16((a), (b), (c), 0, 0, 0)
; __device__ __forceinline__ void gla_phase(LAS unsigned char* lds, const bf16_t* P, const float* hn, bf16_t* O, int G, int wg) {
;     ...
;             { bf16x8 aM[2], vO[4][2], kD[2], vX[4][2];
; #pragma unroll
;               for (int ks = 0; ks < 2; ++ks) { aM[ks] = FRAGS(AM, tt, ks);
; #pragma unroll
;                 for (int i = 0; i < 4; ++i) vO[i][ks] = FRAGS(VT, eh * 4 + i, ks); }
;               __builtin_amdgcn_sched_barrier(0);
; #pragma unroll
;               for (int ks = 0; ks < 2; ++ks) { kD[ks] = FRAGS(KTT, wid, ks);
; #pragma unroll
;                 for (int i = 0; i < 4; ++i) vX[i][ks] = FRAGS(VT, (eh ^ 1) * 4 + i, ks); }
; #pragma unroll
;               for (int i = 0; i < 4; ++i)
; #pragma unroll
;                 for (int ks = 0; ks < 2; ++ks) oacc[i] = MFMA16(vO[i][ks], aM[ks], oacc[i]);
;               __builtin_amdgcn_sched_barrier(0);
;               f32x4 dec4, cl4;
;               { f32x4 bm4 = (f32x4){0.f, 0.f, 0.f, 0.f}, bl4 = (f32x4){0.f, 0.f, 0.f, 0.f};
; #pragma unroll
;                 for (int s2 = 0; s2 < 8; ++s2) { const f32x4 p = *(const LAS f32x4*)(lds + PART + (s2 * 128 + wid * 16 + fq * 4) * 4); if (s2 < 4) bm4 += p; bl4 += p; }
; #pragma unroll
;                 for (int j = 0; j < 4; ++j) { dec4[j] = __builtin_amdgcn_exp2f(bl4[j]); cl4[j] = __builtin_amdgcn_exp2f(bl4[j] - bm4[j]); } }
; #pragma unroll
;               for (int e = 0; e < 8; ++e) { f32x4 tmp = (f32x4){0.f, 0.f, 0.f, 0.f};
; #pragma unroll
;                 for (int ks = 0; ks < 2; ++ks) tmp = MFMA16(kD[ks], (e < 4) ? vO[e & 3][ks] : vX[e & 3][ks], tmp);
;                 sacc[e] = sacc[e] * dec4 + tmp * cl4; }
;             }
;             { float s = 0.f;
; #pragma unroll
;               for (int i = 0; i < 4; ++i) s += (oacc[i][0] * oacc[i][0] + oacc[i][1] * oacc[i][1]) + (oacc[i][2] * oacc[i][2] + oacc[i][3] * oacc[i][3]);
;               s += __shfl_xor(s, 16); s += __shfl_xor(s, 32);
;               if (fq == 0) ((LAS float*)(lds + SSQX))[eh * 64 + tt * 16 + fr] = s; }
	s_waitcnt lgkmcnt(9)
	v_mfma_f32_16x16x32_bf16 v[24:27], v[56:59], v[0:3], 0
	s_waitcnt lgkmcnt(8)
	v_mfma_f32_16x16x32_bf16 v[0:3], v[60:63], v[0:3], 0
	v_mfma_f32_16x16x32_bf16 v[20:23], v[36:39], v[4:7], v[20:23]
	v_mfma_f32_16x16x32_bf16 v[16:19], v[40:43], v[8:11], v[16:19]
	s_waitcnt lgkmcnt(7)
	v_mfma_f32_16x16x32_bf16 v[24:27], v[64:67], v[4:7], v[24:27]
	s_waitcnt lgkmcnt(6)
	v_mfma_f32_16x16x32_bf16 v[0:3], v[68:71], v[4:7], v[0:3]
	v_add_u32_e32 v4, v153, v87
	ds_read_b128 v[28:31], v4
	v_add_u32_e32 v4, v154, v87
	v_mfma_f32_16x16x32_bf16 v[20:23], v[44:47], v[8:11], v[20:23]
	ds_read_b128 v[32:35], v4
	ds_read_b128 v[36:39], v4 offset:2048
	ds_read_b128 v[40:43], v4 offset:4096
	ds_read_b128 v[44:47], v4 offset:6144
	v_add_u32_e32 v4, v153, v160
	v_mfma_f32_16x16x32_bf16 v[16:19], v[48:51], v[12:15], v[16:19]
	ds_read_b128 v[48:51], v4
	v_add_u32_e32 v4, v154, v160
	s_waitcnt lgkmcnt(11)
	v_mfma_f32_16x16x32_bf16 v[24:27], v[72:75], v[8:11], v[24:27]
	s_waitcnt lgkmcnt(10)
	v_mfma_f32_16x16x32_bf16 v[0:3], v[76:79], v[8:11], v[0:3]
	v_mfma_f32_16x16x32_bf16 v[20:23], v[52:55], v[12:15], v[20:23]
	ds_read_b128 v[52:55], v4
	ds_read_b128 v[64:67], v4 offset:2048
	ds_read_b128 v[68:71], v4 offset:4096
	ds_read_b128 v[72:75], v4 offset:6144
	s_waitcnt lgkmcnt(13)
	v_mfma_f32_16x16x32_bf16 v[24:27], v[218:221], v[12:15], v[24:27]
	s_waitcnt lgkmcnt(12)
	v_mfma_f32_16x16x32_bf16 v[0:3], v[222:225], v[12:15], v[0:3]
	s_waitcnt lgkmcnt(8)
	v_mfma_f32_16x16x32_bf16 v[4:7], v[32:35], v[28:31], v[16:19]
	s_waitcnt lgkmcnt(3)
	v_mfma_f32_16x16x32_bf16 v[12:15], v[52:55], v[48:51], v[4:7]
	s_nop 0
	v_add_u32_e32 v16, v155, v87
	ds_read_b128 v[218:221], v16
	ds_read_b128 v[76:79], v182
	ds_read_b128 v[222:225], v182 offset:2048
	ds_read_b128 v[226:229], v182 offset:4096
	v_add_u32_e32 v16, v155, v160
	v_mfma_f32_16x16x32_bf16 v[4:7], v[36:39], v[28:31], v[20:23]
	ds_read_b128 v[230:233], v182 offset:6144
	ds_read_b128 v[234:237], v16
	ds_read_b128 v[238:241], v183
	ds_read_b128 v[242:245], v183 offset:2048
	ds_read_b128 v[246:249], v183 offset:4096
	ds_read_b128 v[176:179], v183 offset:6144
	s_waitcnt lgkmcnt(12)
	v_mfma_f32_16x16x32_bf16 v[8:11], v[64:67], v[48:51], v[4:7]
	v_mfma_f32_16x16x32_bf16 v[4:7], v[40:43], v[28:31], v[24:27]
	v_mfma_f32_16x16x32_bf16 v[0:3], v[44:47], v[28:31], v[0:3]
	s_waitcnt lgkmcnt(11)
	v_mfma_f32_16x16x32_bf16 v[4:7], v[68:71], v[48:51], v[4:7]
	s_waitcnt lgkmcnt(10)
	v_mfma_f32_16x16x32_bf16 v[0:3], v[72:75], v[48:51], v[0:3]
	v_mul_f32_e32 v24, v13, v13
	v_mul_f32_e32 v25, v15, v15
	v_fmac_f32_e32 v24, v12, v12
	v_fmac_f32_e32 v25, v14, v14
	v_mul_f32_e32 v29, v9, v9
	v_mul_f32_e32 v30, v11, v11
	s_waitcnt lgkmcnt(9)
	v_mfma_f32_16x16x32_bf16 v[16:19], v[218:221], v[32:35], 0
	v_add_f32_e32 v28, v24, v25
	v_fmac_f32_e32 v29, v8, v8
	v_fmac_f32_e32 v30, v10, v10
	v_mfma_f32_16x16x32_bf16 v[24:27], v[218:221], v[40:43], 0
	v_mul_f32_e32 v33, v5, v5
	v_mul_f32_e32 v34, v7, v7
	v_and_b32_e32 v41, 64, v213
	v_mfma_f32_16x16x32_bf16 v[20:23], v[218:221], v[36:39], 0
	v_add_f32_e32 v29, v29, v30
	v_fmac_f32_e32 v33, v4, v4
	v_fmac_f32_e32 v34, v6, v6
	v_mul_f32_e32 v37, v1, v1
	v_mul_f32_e32 v38, v3, v3
	v_xor_b32_e32 v40, 16, v213
	v_add_u32_e32 v173, 64, v41
	v_add_f32_e32 v32, v28, v29
	v_add_f32_e32 v33, v33, v34
	v_fmac_f32_e32 v37, v0, v0
	v_fmac_f32_e32 v38, v2, v2
	v_cmp_lt_i32_e32 vcc, v40, v173
	v_add_f32_e32 v36, v32, v33
	v_add_f32_e32 v37, v37, v38
	v_cndmask_b32_e32 v40, v213, v40, vcc
	v_mfma_f32_16x16x32_bf16 v[28:31], v[218:221], v[44:47], 0
	v_add_f32_e32 v44, v36, v37
	v_lshlrev_b32_e32 v95, 2, v40
	ds_bpermute_b32 v45, v95, v44
	v_xor_b32_e32 v174, 32, v213
	s_waitcnt lgkmcnt(9)
	v_mfma_f32_16x16x32_bf16 v[32:35], v[218:221], v[76:79], 0
	v_cmp_lt_i32_e32 vcc, v174, v173
	ds_read_b128 v[60:63], v184
	ds_read_b128 v[56:59], v184 offset:512
	s_waitcnt lgkmcnt(2)
	v_add_f32_e32 v172, v44, v45
	v_mfma_f32_16x16x32_bf16 v[36:39], v[218:221], v[222:225], 0
	v_cndmask_b32_e32 v173, v213, v174, vcc
	v_lshlrev_b32_e32 v173, 2, v173
	ds_bpermute_b32 v173, v173, v172
	v_mfma_f32_16x16x32_bf16 v[40:43], v[218:221], v[226:229], 0
	v_mfma_f32_16x16x32_bf16 v[44:47], v[218:221], v[230:233], 0
	v_mfma_f32_16x16x32_bf16 v[16:19], v[234:237], v[52:55], v[16:19]
	ds_read_b128 v[52:55], v184 offset:1024
	ds_read_b128 v[48:51], v184 offset:1536
	v_mfma_f32_16x16x32_bf16 v[20:23], v[234:237], v[64:67], v[20:23]
	v_mfma_f32_16x16x32_bf16 v[24:27], v[234:237], v[68:71], v[24:27]
	v_mfma_f32_16x16x32_bf16 v[28:31], v[234:237], v[72:75], v[28:31]
	ds_read_b128 v[76:79], v184 offset:2048
	ds_read_b128 v[72:75], v184 offset:2560
	ds_read_b128 v[68:71], v184 offset:3072
	ds_read_b128 v[64:67], v184 offset:3584
	v_mfma_f32_16x16x32_bf16 v[32:35], v[234:237], v[238:241], v[32:35]
	v_mfma_f32_16x16x32_bf16 v[36:39], v[234:237], v[242:245], v[36:39]
	v_mfma_f32_16x16x32_bf16 v[40:43], v[234:237], v[246:249], v[40:43]
	v_mfma_f32_16x16x32_bf16 v[44:47], v[234:237], v[176:179], v[44:47]
	s_and_saveexec_b64 vcc, s[44:45]
	s_cbranch_execz .LBB0_1401
	s_waitcnt lgkmcnt(6)
	v_add_f32_e32 v172, v172, v173
	ds_write_b32 v156, v172
	s_branch .LBB0_1401
	s_nop 0
	s_nop 0
	s_nop 0
	s_nop 0
	s_nop 0
	s_nop 0
	s_nop 0
	s_nop 0
	s_nop 0
	s_nop 0
	s_nop 0
	s_nop 0
	s_nop 0
	s_nop 0
	s_nop 0
	s_nop 0
	s_nop 0
	s_nop 0
	s_nop 0
	s_nop 0
	s_nop 0
	s_nop 0
	s_nop 0
	s_nop 0
	s_nop 0
	s_nop 0
	s_nop 0
	s_nop 0
	s_nop 0
	s_nop 0
	s_nop 0
	s_nop 0
	s_nop 0
	s_nop 0
	s_nop 0
	s_nop 0
